# S2 mid hook: second half-tile's gate loads issued together with the first half's (free registers), second wait no longer exposes a round trip
# speedup vs baseline: 1.0092x; 1.0074x over previous
.LBB0_826:
	v_lshl_add_u32 v188, s1, 8, v179
	v_lshl_or_b32 v156, s0, 8, v184
	v_lshl_add_u32 v138, v188, 11, v156
	global_load_dwordx2 v[190:191], v138, s[18:19]
	global_load_dwordx2 v[192:193], v138, s[16:17] nt
	v_or_b32_e32 v157, 0x80, v138
	global_load_dwordx2 v[194:195], v157, s[18:19]
	global_load_dwordx2 v[196:197], v157, s[16:17] nt
	v_add_u32_e32 v157, 0x8000, v138
	v_add_u32_e32 v158, 0x8080, v138
	v_add_u32_e32 v159, 0x10000, v138
	v_add_u32_e32 v160, 0x10080, v138
	v_add_u32_e32 v161, 0x18000, v138
	v_add_u32_e32 v189, 0x18080, v138
	global_load_dwordx2 v[182:183], v157, s[16:17] nt
	global_load_dwordx2 v[198:199], v157, s[18:19]
	global_load_dwordx2 v[174:175], v158, s[16:17] nt
	global_load_dwordx2 v[176:177], v158, s[18:19]
	global_load_dwordx2 v[170:171], v159, s[16:17] nt
	global_load_dwordx2 v[172:173], v159, s[18:19]
	global_load_dwordx2 v[166:167], v160, s[16:17] nt
	global_load_dwordx2 v[168:169], v160, s[18:19]
	global_load_dwordx2 v[162:163], v161, s[16:17] nt
	global_load_dwordx2 v[164:165], v161, s[18:19]
	s_nop 0
	global_load_dwordx2 v[158:159], v189, s[16:17] nt
	global_load_dwordx2 v[160:161], v189, s[18:19]
	v_add_u32_e32 v219, 0x40000, v138
	v_add_u32_e32 v220, 0x48000, v138
	v_add_u32_e32 v221, 0x50000, v138
	v_add_u32_e32 v247, 0x58000, v138
	global_load_dwordx2 v[222:223], v219, s[16:17] nt
	global_load_dwordx2 v[224:225], v219, s[18:19]
	global_load_dwordx2 v[226:227], v219, s[16:17] offset:128 nt
	global_load_dwordx2 v[228:229], v219, s[18:19] offset:128
	global_load_dwordx2 v[230:231], v220, s[16:17] nt
	global_load_dwordx2 v[232:233], v220, s[18:19]
	global_load_dwordx2 v[234:235], v220, s[16:17] offset:128 nt
	global_load_dwordx2 v[236:237], v220, s[18:19] offset:128
	global_load_dwordx2 v[238:239], v221, s[16:17] nt
	global_load_dwordx2 v[240:241], v221, s[18:19]
	global_load_dwordx2 v[242:243], v221, s[16:17] offset:128 nt
	global_load_dwordx2 v[244:245], v221, s[18:19] offset:128
	global_load_dwordx2 v[248:249], v247, s[16:17] nt
	global_load_dwordx2 v[250:251], v247, s[18:19]
	global_load_dwordx2 v[252:253], v247, s[16:17] offset:128 nt
	global_load_dwordx2 v[254:255], v247, s[18:19] offset:128
	s_and_b64 s[0:1], s[42:43], exec
	s_cselect_b32 s13, s56, s13
	s_cselect_b32 s12, s55, s12
	s_cmp_ge_i32 s40, s51
	s_waitcnt vmcnt(16)
	v_cvt_f32_ubyte0_e32 v157, v190
	v_cvt_f32_ubyte1_e32 v189, v190
	v_cvt_f32_ubyte2_e32 v206, v190
	v_cvt_f32_ubyte3_e32 v207, v190
	v_cvt_f32_ubyte0_e32 v208, v191
	v_cvt_f32_ubyte1_e32 v209, v191
	v_cvt_f32_ubyte2_e32 v210, v191
	v_cvt_f32_ubyte3_e32 v211, v191
	v_cvt_f32_ubyte3_e32 v201, v192
	v_cvt_f32_ubyte2_e32 v200, v192
	v_cvt_f32_ubyte3_e32 v205, v193
	v_cvt_f32_ubyte2_e32 v204, v193
	v_mul_f32_e32 v157, 0x3b808081, v157
	v_mul_f32_e32 v189, 0x3b808081, v189
	v_cvt_f32_ubyte1_e32 v191, v192
	v_cvt_f32_ubyte0_e32 v190, v192
	v_cvt_f32_ubyte1_e32 v203, v193
	v_cvt_f32_ubyte0_e32 v202, v193
	v_mul_f32_e32 v206, 0x3b808081, v206
	v_mul_f32_e32 v207, 0x3b808081, v207
	v_mul_f32_e32 v208, 0x3b808081, v208
	v_mul_f32_e32 v209, 0x3b808081, v209
	v_mul_f32_e32 v210, 0x3b808081, v210
	v_mul_f32_e32 v211, 0x3b808081, v211
	v_pk_mul_f32 v[192:193], v[200:201], s[30:31] op_sel_hi:[1,0]
	v_pk_mul_f32 v[200:201], v[204:205], s[30:31] op_sel_hi:[1,0]
	v_cvt_f32_ubyte0_e32 v204, v194
	v_cvt_f32_ubyte1_e32 v205, v194
	v_max_f32_e32 v157, 0x21800000, v157
	v_max_f32_e32 v189, 0x21800000, v189
	v_max_f32_e32 v208, 0x21800000, v208
	v_max_f32_e32 v209, 0x21800000, v209
	v_max_f32_e32 v214, 0x21800000, v206
	v_max_f32_e32 v210, 0x21800000, v210
	v_max_f32_e32 v215, 0x21800000, v207
	v_max_f32_e32 v211, 0x21800000, v211
	v_mul_f32_e32 v216, 0x3b808081, v204
	v_mul_f32_e32 v217, 0x3b808081, v205
	v_rcp_f32_e32 v204, v157
	v_rcp_f32_e32 v205, v189
	v_rcp_f32_e32 v206, v208
	v_rcp_f32_e32 v207, v209
	v_rcp_f32_e32 v208, v214
	v_rcp_f32_e32 v209, v215
	v_rcp_f32_e32 v210, v210
	v_rcp_f32_e32 v211, v211
	v_pk_mul_f32 v[190:191], v[190:191], s[30:31] op_sel_hi:[1,0]
	v_cvt_f32_ubyte2_e32 v212, v194
	v_cvt_f32_ubyte3_e32 v194, v194
	v_cvt_f32_ubyte0_e32 v213, v195
	v_cvt_f32_ubyte1_e32 v157, v195
	v_mul_f32_e32 v218, 0x3b808081, v194
	v_mul_f32_e32 v194, 0x3b808081, v213
	v_pk_mul_f32 v[190:191], v[190:191], v[204:205]
	v_mul_f32_e32 v157, 0x3b808081, v157
	v_mul_f32_e32 v212, 0x3b808081, v212
	v_pk_mul_f32 v[192:193], v[192:193], v[208:209]
	v_pk_mul_f32 v[200:201], v[200:201], v[210:211]
	v_pk_mul_f32 v[70:71], v[70:71], v[190:191]
	v_cvt_f32_ubyte2_e32 v189, v195
	v_cvt_f32_ubyte3_e32 v190, v195
	v_max_f32_e32 v191, 0x21800000, v194
	v_max_f32_e32 v157, 0x21800000, v157
	v_pk_mul_f32 v[72:73], v[72:73], v[192:193]
	v_pk_mul_f32 v[68:69], v[68:69], v[200:201]
	v_mul_f32_e32 v189, 0x3b808081, v189
	v_mul_f32_e32 v201, 0x3b808081, v190
	v_max_f32_e32 v190, 0x21800000, v216
	v_rcp_f32_e32 v192, v191
	v_max_f32_e32 v191, 0x21800000, v217
	v_rcp_f32_e32 v193, v157
	v_max_f32_e32 v157, 0x21800000, v212
	v_pk_mul_f32 v[202:203], v[202:203], s[30:31] op_sel_hi:[1,0]
	v_rcp_f32_e32 v190, v190
	v_rcp_f32_e32 v191, v191
	v_rcp_f32_e32 v194, v157
	v_max_f32_e32 v157, 0x21800000, v189
	v_pk_mul_f32 v[202:203], v[202:203], v[206:207]
	v_rcp_f32_e32 v200, v157
	v_max_f32_e32 v157, 0x21800000, v218
	v_pk_mul_f32 v[66:67], v[66:67], v[202:203]
	v_rcp_f32_e32 v195, v157
	v_cvt_f32_ubyte1_e32 v203, v196
	v_cvt_f32_ubyte0_e32 v202, v196
	v_pk_mul_f32 v[202:203], v[202:203], s[30:31] op_sel_hi:[1,0]
	v_cvt_f32_ubyte3_e32 v205, v196
	v_cvt_f32_ubyte2_e32 v204, v196
	v_pk_mul_f32 v[190:191], v[202:203], v[190:191]
	v_max_f32_e32 v157, 0x21800000, v201
	v_pk_mul_f32 v[204:205], v[204:205], s[30:31] op_sel_hi:[1,0]
	v_pk_mul_f32 v[74:75], v[74:75], v[190:191]
	v_rcp_f32_e32 v201, v157
	v_cvt_f32_ubyte1_e32 v191, v197
	v_cvt_f32_ubyte0_e32 v190, v197
	v_pk_mul_f32 v[194:195], v[204:205], v[194:195]
	v_pk_mul_f32 v[190:191], v[190:191], s[30:31] op_sel_hi:[1,0]
	v_pk_mul_f32 v[76:77], v[76:77], v[194:195]
	v_cvt_f32_ubyte3_e32 v195, v197
	v_cvt_f32_ubyte2_e32 v194, v197
	v_pk_mul_f32 v[190:191], v[190:191], v[192:193]
	v_pk_mul_f32 v[194:195], v[194:195], s[30:31] op_sel_hi:[1,0]
	v_pk_mul_f32 v[82:83], v[82:83], v[190:191]
	v_cvt_f32_ubyte2_e32 v190, v198
	v_pk_mul_f32 v[192:193], v[194:195], v[200:201]
	v_mul_f32_e32 v194, 0x3b808081, v190
	v_cvt_f32_ubyte3_e32 v190, v198
	v_mul_f32_e32 v195, 0x3b808081, v190
	v_cvt_f32_ubyte0_e32 v190, v199
	v_cvt_f32_ubyte0_e32 v157, v198
	v_mul_f32_e32 v191, 0x3b808081, v190
	v_cvt_f32_ubyte1_e32 v190, v199
	v_pk_mul_f32 v[84:85], v[84:85], v[192:193]
	v_mul_f32_e32 v157, 0x3b808081, v157
	v_mul_f32_e32 v193, 0x3b808081, v190
	v_cvt_f32_ubyte2_e32 v190, v199
	v_cvt_f32_ubyte1_e32 v189, v198
	v_mul_f32_e32 v196, 0x3b808081, v190
	v_cvt_f32_ubyte3_e32 v190, v199
	v_max_f32_e32 v157, 0x21800000, v157
	v_mul_f32_e32 v189, 0x3b808081, v189
	v_mul_f32_e32 v197, 0x3b808081, v190
	v_rcp_f32_e32 v190, v157
	v_max_f32_e32 v157, 0x21800000, v191
	v_rcp_f32_e32 v192, v157
	v_max_f32_e32 v157, 0x21800000, v189
	v_rcp_f32_e32 v191, v157
	v_max_f32_e32 v157, 0x21800000, v193
	v_rcp_f32_e32 v193, v157
	v_max_f32_e32 v157, 0x21800000, v194
	v_rcp_f32_e32 v194, v157
	v_max_f32_e32 v157, 0x21800000, v196
	v_rcp_f32_e32 v196, v157
	v_max_f32_e32 v157, 0x21800000, v195
	v_rcp_f32_e32 v195, v157
	v_cvt_f32_ubyte3_e32 v201, v182
	v_cvt_f32_ubyte2_e32 v200, v182
	v_max_f32_e32 v157, 0x21800000, v197
	v_cvt_f32_ubyte1_e32 v199, v182
	v_cvt_f32_ubyte0_e32 v198, v182
	v_pk_mul_f32 v[200:201], v[200:201], s[30:31] op_sel_hi:[1,0]
	v_rcp_f32_e32 v197, v157
	v_pk_mul_f32 v[198:199], v[198:199], s[30:31] op_sel_hi:[1,0]
	v_pk_mul_f32 v[194:195], v[200:201], v[194:195]
	v_pk_mul_f32 v[190:191], v[198:199], v[190:191]
	v_pk_mul_f32 v[88:89], v[88:89], v[194:195]
	v_cvt_f32_ubyte3_e32 v195, v183
	v_cvt_f32_ubyte2_e32 v194, v183
	v_pk_mul_f32 v[86:87], v[86:87], v[190:191]
	v_cvt_f32_ubyte1_e32 v191, v183
	v_cvt_f32_ubyte0_e32 v190, v183
	v_pk_mul_f32 v[182:183], v[194:195], s[30:31] op_sel_hi:[1,0]
	v_pk_mul_f32 v[190:191], v[190:191], s[30:31] op_sel_hi:[1,0]
	v_pk_mul_f32 v[182:183], v[182:183], v[196:197]
	v_pk_mul_f32 v[190:191], v[190:191], v[192:193]
	v_pk_mul_f32 v[96:97], v[96:97], v[182:183]
	v_cvt_f32_ubyte1_e32 v182, v176
	v_cvt_f32_ubyte0_e32 v157, v176
	v_mul_f32_e32 v183, 0x3b808081, v182
	v_cvt_f32_ubyte2_e32 v182, v176
	v_cvt_f32_ubyte3_e32 v176, v176
	v_pk_mul_f32 v[94:95], v[94:95], v[190:191]
	v_mul_f32_e32 v191, 0x3b808081, v176
	v_cvt_f32_ubyte0_e32 v176, v177
	v_mul_f32_e32 v189, 0x3b808081, v182
	v_mul_f32_e32 v182, 0x3b808081, v176
	v_cvt_f32_ubyte1_e32 v176, v177
	v_mul_f32_e32 v157, 0x3b808081, v157
	v_mul_f32_e32 v190, 0x3b808081, v176
	v_cvt_f32_ubyte2_e32 v176, v177
	v_mul_f32_e32 v192, 0x3b808081, v176
	v_cvt_f32_ubyte3_e32 v176, v177
	v_max_f32_e32 v157, 0x21800000, v157
	v_mul_f32_e32 v193, 0x3b808081, v176
	v_rcp_f32_e32 v176, v157
	v_max_f32_e32 v157, 0x21800000, v182
	v_rcp_f32_e32 v182, v157
	v_max_f32_e32 v157, 0x21800000, v183
	v_rcp_f32_e32 v177, v157
	v_max_f32_e32 v157, 0x21800000, v190
	v_rcp_f32_e32 v183, v157
	v_max_f32_e32 v157, 0x21800000, v189
	v_rcp_f32_e32 v190, v157
	v_max_f32_e32 v157, 0x21800000, v192
	v_rcp_f32_e32 v192, v157
	v_max_f32_e32 v157, 0x21800000, v191
	v_rcp_f32_e32 v191, v157
	v_cvt_f32_ubyte3_e32 v197, v174
	v_cvt_f32_ubyte2_e32 v196, v174
	v_max_f32_e32 v157, 0x21800000, v193
	v_cvt_f32_ubyte1_e32 v195, v174
	v_cvt_f32_ubyte0_e32 v194, v174
	v_pk_mul_f32 v[196:197], v[196:197], s[30:31] op_sel_hi:[1,0]
	v_rcp_f32_e32 v193, v157
	v_pk_mul_f32 v[194:195], v[194:195], s[30:31] op_sel_hi:[1,0]
	v_pk_mul_f32 v[190:191], v[196:197], v[190:191]
	v_pk_mul_f32 v[176:177], v[194:195], v[176:177]
	v_pk_mul_f32 v[100:101], v[100:101], v[190:191]
	v_cvt_f32_ubyte3_e32 v191, v175
	v_cvt_f32_ubyte2_e32 v190, v175
	v_pk_mul_f32 v[98:99], v[98:99], v[176:177]
	v_cvt_f32_ubyte1_e32 v177, v175
	v_cvt_f32_ubyte0_e32 v176, v175
	v_pk_mul_f32 v[174:175], v[190:191], s[30:31] op_sel_hi:[1,0]
	v_pk_mul_f32 v[176:177], v[176:177], s[30:31] op_sel_hi:[1,0]
	v_pk_mul_f32 v[174:175], v[174:175], v[192:193]
	v_pk_mul_f32 v[176:177], v[176:177], v[182:183]
	v_pk_mul_f32 v[108:109], v[108:109], v[174:175]
	v_cvt_f32_ubyte1_e32 v174, v172
	v_cvt_f32_ubyte0_e32 v157, v172
	v_mul_f32_e32 v175, 0x3b808081, v174
	v_cvt_f32_ubyte2_e32 v174, v172
	v_cvt_f32_ubyte3_e32 v172, v172
	v_pk_mul_f32 v[106:107], v[106:107], v[176:177]
	v_mul_f32_e32 v177, 0x3b808081, v172
	v_cvt_f32_ubyte0_e32 v172, v173
	v_mul_f32_e32 v176, 0x3b808081, v174
	v_mul_f32_e32 v174, 0x3b808081, v172
	v_cvt_f32_ubyte1_e32 v172, v173
	v_mul_f32_e32 v157, 0x3b808081, v157
	v_mul_f32_e32 v182, 0x3b808081, v172
	v_cvt_f32_ubyte2_e32 v172, v173
	v_mul_f32_e32 v183, 0x3b808081, v172
	v_cvt_f32_ubyte3_e32 v172, v173
	v_max_f32_e32 v157, 0x21800000, v157
	v_mul_f32_e32 v189, 0x3b808081, v172
	v_rcp_f32_e32 v172, v157
	v_max_f32_e32 v157, 0x21800000, v174
	v_rcp_f32_e32 v174, v157
	v_max_f32_e32 v157, 0x21800000, v175
	v_rcp_f32_e32 v173, v157
	v_max_f32_e32 v157, 0x21800000, v182
	v_rcp_f32_e32 v175, v157
	v_max_f32_e32 v157, 0x21800000, v176
	v_rcp_f32_e32 v176, v157
	v_max_f32_e32 v157, 0x21800000, v183
	v_rcp_f32_e32 v182, v157
	v_max_f32_e32 v157, 0x21800000, v177
	v_rcp_f32_e32 v177, v157
	v_cvt_f32_ubyte3_e32 v193, v170
	v_cvt_f32_ubyte2_e32 v192, v170
	v_max_f32_e32 v157, 0x21800000, v189
	v_cvt_f32_ubyte1_e32 v191, v170
	v_cvt_f32_ubyte0_e32 v190, v170
	v_pk_mul_f32 v[192:193], v[192:193], s[30:31] op_sel_hi:[1,0]
	v_rcp_f32_e32 v183, v157
	v_pk_mul_f32 v[190:191], v[190:191], s[30:31] op_sel_hi:[1,0]
	v_pk_mul_f32 v[176:177], v[192:193], v[176:177]
	v_pk_mul_f32 v[172:173], v[190:191], v[172:173]
	v_pk_mul_f32 v[112:113], v[112:113], v[176:177]
	v_cvt_f32_ubyte3_e32 v177, v171
	v_cvt_f32_ubyte2_e32 v176, v171
	v_pk_mul_f32 v[110:111], v[110:111], v[172:173]
	v_cvt_f32_ubyte1_e32 v173, v171
	v_cvt_f32_ubyte0_e32 v172, v171
	v_pk_mul_f32 v[170:171], v[176:177], s[30:31] op_sel_hi:[1,0]
	v_pk_mul_f32 v[172:173], v[172:173], s[30:31] op_sel_hi:[1,0]
	v_pk_mul_f32 v[170:171], v[170:171], v[182:183]
	v_pk_mul_f32 v[172:173], v[172:173], v[174:175]
	v_pk_mul_f32 v[116:117], v[116:117], v[170:171]
	v_cvt_f32_ubyte1_e32 v170, v168
	v_cvt_f32_ubyte0_e32 v157, v168
	v_mul_f32_e32 v171, 0x3b808081, v170
	v_cvt_f32_ubyte2_e32 v170, v168
	v_cvt_f32_ubyte3_e32 v168, v168
	v_pk_mul_f32 v[114:115], v[114:115], v[172:173]
	v_mul_f32_e32 v173, 0x3b808081, v168
	v_cvt_f32_ubyte0_e32 v168, v169
	v_mul_f32_e32 v172, 0x3b808081, v170
	v_mul_f32_e32 v170, 0x3b808081, v168
	v_cvt_f32_ubyte1_e32 v168, v169
	v_mul_f32_e32 v157, 0x3b808081, v157
	v_mul_f32_e32 v174, 0x3b808081, v168
	v_cvt_f32_ubyte2_e32 v168, v169
	v_mul_f32_e32 v175, 0x3b808081, v168
	v_cvt_f32_ubyte3_e32 v168, v169
	v_max_f32_e32 v157, 0x21800000, v157
	v_mul_f32_e32 v189, 0x3b808081, v168
	v_rcp_f32_e32 v168, v157
	v_max_f32_e32 v157, 0x21800000, v170
	v_rcp_f32_e32 v170, v157
	v_max_f32_e32 v157, 0x21800000, v171
	v_rcp_f32_e32 v169, v157
	v_max_f32_e32 v157, 0x21800000, v174
	v_rcp_f32_e32 v171, v157
	v_max_f32_e32 v157, 0x21800000, v172
	v_rcp_f32_e32 v172, v157
	v_max_f32_e32 v157, 0x21800000, v175
	v_rcp_f32_e32 v174, v157
	v_max_f32_e32 v157, 0x21800000, v173
	v_rcp_f32_e32 v173, v157
	v_cvt_f32_ubyte3_e32 v183, v166
	v_cvt_f32_ubyte2_e32 v182, v166
	v_max_f32_e32 v157, 0x21800000, v189
	v_cvt_f32_ubyte1_e32 v177, v166
	v_cvt_f32_ubyte0_e32 v176, v166
	v_pk_mul_f32 v[182:183], v[182:183], s[30:31] op_sel_hi:[1,0]
	v_rcp_f32_e32 v175, v157
	v_pk_mul_f32 v[176:177], v[176:177], s[30:31] op_sel_hi:[1,0]
	v_pk_mul_f32 v[172:173], v[182:183], v[172:173]
	v_pk_mul_f32 v[168:169], v[176:177], v[168:169]
	v_pk_mul_f32 v[120:121], v[120:121], v[172:173]
	v_cvt_f32_ubyte3_e32 v173, v167
	v_cvt_f32_ubyte2_e32 v172, v167
	v_pk_mul_f32 v[118:119], v[118:119], v[168:169]
	v_cvt_f32_ubyte1_e32 v169, v167
	v_cvt_f32_ubyte0_e32 v168, v167
	v_pk_mul_f32 v[166:167], v[172:173], s[30:31] op_sel_hi:[1,0]
	v_pk_mul_f32 v[168:169], v[168:169], s[30:31] op_sel_hi:[1,0]
	v_pk_mul_f32 v[166:167], v[166:167], v[174:175]
	v_pk_mul_f32 v[168:169], v[168:169], v[170:171]
	v_pk_mul_f32 v[124:125], v[124:125], v[166:167]
	v_cvt_f32_ubyte1_e32 v166, v164
	v_cvt_f32_ubyte0_e32 v157, v164
	v_mul_f32_e32 v167, 0x3b808081, v166
	v_cvt_f32_ubyte2_e32 v166, v164
	v_cvt_f32_ubyte3_e32 v164, v164
	v_pk_mul_f32 v[122:123], v[122:123], v[168:169]
	v_mul_f32_e32 v169, 0x3b808081, v164
	v_cvt_f32_ubyte0_e32 v164, v165
	v_mul_f32_e32 v168, 0x3b808081, v166
	v_mul_f32_e32 v166, 0x3b808081, v164
	v_cvt_f32_ubyte1_e32 v164, v165
	v_mul_f32_e32 v157, 0x3b808081, v157
	v_mul_f32_e32 v170, 0x3b808081, v164
	v_cvt_f32_ubyte2_e32 v164, v165
	v_mul_f32_e32 v171, 0x3b808081, v164
	v_cvt_f32_ubyte3_e32 v164, v165
	v_max_f32_e32 v157, 0x21800000, v157
	v_mul_f32_e32 v176, 0x3b808081, v164
	v_rcp_f32_e32 v164, v157
	v_max_f32_e32 v157, 0x21800000, v166
	v_rcp_f32_e32 v166, v157
	v_max_f32_e32 v157, 0x21800000, v167
	v_rcp_f32_e32 v165, v157
	v_max_f32_e32 v157, 0x21800000, v170
	v_rcp_f32_e32 v167, v157
	v_max_f32_e32 v157, 0x21800000, v168
	v_rcp_f32_e32 v168, v157
	v_max_f32_e32 v157, 0x21800000, v171
	v_rcp_f32_e32 v170, v157
	v_max_f32_e32 v157, 0x21800000, v169
	v_rcp_f32_e32 v169, v157
	v_max_f32_e32 v157, 0x21800000, v176
	v_cvt_f32_ubyte3_e32 v175, v162
	v_cvt_f32_ubyte2_e32 v174, v162
	v_rcp_f32_e32 v171, v157
	v_add_u32_e32 v157, 0x40000, v138
	v_cvt_f32_ubyte1_e32 v173, v162
	v_cvt_f32_ubyte0_e32 v172, v162
	v_pk_mul_f32 v[174:175], v[174:175], s[30:31] op_sel_hi:[1,0]
	v_pk_mul_f32 v[172:173], v[172:173], s[30:31] op_sel_hi:[1,0]
	v_pk_mul_f32 v[168:169], v[174:175], v[168:169]
	v_pk_mul_f32 v[164:165], v[172:173], v[164:165]
	v_pk_mul_f32 v[128:129], v[128:129], v[168:169]
	v_cvt_f32_ubyte3_e32 v169, v163
	v_cvt_f32_ubyte2_e32 v168, v163
	v_pk_mul_f32 v[126:127], v[126:127], v[164:165]
	v_cvt_f32_ubyte1_e32 v165, v163
	v_cvt_f32_ubyte0_e32 v164, v163
	v_pk_mul_f32 v[162:163], v[168:169], s[30:31] op_sel_hi:[1,0]
	v_pk_mul_f32 v[164:165], v[164:165], s[30:31] op_sel_hi:[1,0]
	v_pk_mul_f32 v[162:163], v[162:163], v[170:171]
	v_pk_mul_f32 v[164:165], v[164:165], v[166:167]
	v_pk_mul_f32 v[104:105], v[104:105], v[162:163]
	v_cvt_f32_ubyte1_e32 v162, v160
	v_cvt_f32_ubyte0_e32 v157, v160
	v_mul_f32_e32 v163, 0x3b808081, v162
	v_cvt_f32_ubyte2_e32 v162, v160
	v_cvt_f32_ubyte3_e32 v160, v160
	v_pk_mul_f32 v[102:103], v[102:103], v[164:165]
	v_mul_f32_e32 v165, 0x3b808081, v160
	v_cvt_f32_ubyte0_e32 v160, v161
	v_mul_f32_e32 v164, 0x3b808081, v162
	v_mul_f32_e32 v162, 0x3b808081, v160
	v_cvt_f32_ubyte1_e32 v160, v161
	v_mul_f32_e32 v157, 0x3b808081, v157
	v_mul_f32_e32 v166, 0x3b808081, v160
	v_cvt_f32_ubyte2_e32 v160, v161
	v_mul_f32_e32 v167, 0x3b808081, v160
	v_cvt_f32_ubyte3_e32 v160, v161
	v_max_f32_e32 v157, 0x21800000, v157
	v_mul_f32_e32 v172, 0x3b808081, v160
	v_rcp_f32_e32 v160, v157
	v_max_f32_e32 v157, 0x21800000, v162
	v_rcp_f32_e32 v162, v157
	v_max_f32_e32 v157, 0x21800000, v163
	v_rcp_f32_e32 v161, v157
	v_max_f32_e32 v157, 0x21800000, v166
	v_rcp_f32_e32 v163, v157
	v_max_f32_e32 v157, 0x21800000, v164
	v_rcp_f32_e32 v164, v157
	v_max_f32_e32 v157, 0x21800000, v167
	v_rcp_f32_e32 v166, v157
	v_max_f32_e32 v157, 0x21800000, v165
	v_rcp_f32_e32 v165, v157
	v_max_f32_e32 v157, 0x21800000, v172
	v_rcp_f32_e32 v167, v157
	v_add_u32_e32 v157, 0x40080, v138
	v_cvt_f32_ubyte3_e32 v171, v158
	v_cvt_f32_ubyte2_e32 v170, v158
	v_cvt_f32_ubyte1_e32 v169, v158
	v_cvt_f32_ubyte0_e32 v168, v158
	v_pk_mul_f32 v[170:171], v[170:171], s[30:31] op_sel_hi:[1,0]
	v_pk_mul_f32 v[168:169], v[168:169], s[30:31] op_sel_hi:[1,0]
	v_pk_mul_f32 v[164:165], v[170:171], v[164:165]
	v_pk_mul_f32 v[160:161], v[168:169], v[160:161]
	v_pk_mul_f32 v[92:93], v[92:93], v[164:165]
	v_cvt_f32_ubyte3_e32 v165, v159
	v_cvt_f32_ubyte2_e32 v164, v159
	v_pk_mul_f32 v[90:91], v[90:91], v[160:161]
	v_cvt_f32_ubyte1_e32 v161, v159
	v_cvt_f32_ubyte0_e32 v160, v159
	v_pk_mul_f32 v[158:159], v[164:165], s[30:31] op_sel_hi:[1,0]
	v_add_u32_e32 v157, 0x48000, v138
	v_pk_mul_f32 v[158:159], v[158:159], v[166:167]
	v_pk_mul_f32 v[160:161], v[160:161], s[30:31] op_sel_hi:[1,0]
	v_pk_mul_f32 v[80:81], v[80:81], v[158:159]
	v_add_u32_e32 v158, 0x48080, v138
	v_add_u32_e32 v157, 0x50000, v138
	v_add_u32_e32 v158, 0x50080, v138
	v_pk_mul_f32 v[160:161], v[160:161], v[162:163]
	v_add_u32_e32 v157, 0x58000, v138
	v_add_u32_e32 v138, 0x58080, v138
	v_pk_mul_f32 v[78:79], v[78:79], v[160:161]
	s_waitcnt vmcnt(0)
	v_mov_b64_e32 v[182:183], v[222:223]
	v_mov_b64_e32 v[190:191], v[224:225]
	v_mov_b64_e32 v[192:193], v[226:227]
	v_mov_b64_e32 v[194:195], v[228:229]
	v_mov_b64_e32 v[196:197], v[230:231]
	v_mov_b64_e32 v[198:199], v[232:233]
	v_mov_b64_e32 v[174:175], v[234:235]
	v_mov_b64_e32 v[176:177], v[236:237]
	v_mov_b64_e32 v[170:171], v[238:239]
	v_mov_b64_e32 v[172:173], v[240:241]
	v_mov_b64_e32 v[166:167], v[242:243]
	v_mov_b64_e32 v[168:169], v[244:245]
	v_mov_b64_e32 v[162:163], v[248:249]
	v_mov_b64_e32 v[164:165], v[250:251]
	v_mov_b64_e32 v[158:159], v[252:253]
	v_mov_b64_e32 v[160:161], v[254:255]
	s_nop 1
	v_cvt_f32_ubyte3_e32 v209, v182
	v_cvt_f32_ubyte0_e32 v138, v190
	v_cvt_f32_ubyte1_e32 v157, v190
	v_cvt_f32_ubyte2_e32 v189, v190
	v_cvt_f32_ubyte3_e32 v190, v190
	v_mul_f32_e32 v203, 0x3b808081, v190
	v_cvt_f32_ubyte0_e32 v190, v191
	v_mul_f32_e32 v200, 0x3b808081, v190
	v_cvt_f32_ubyte1_e32 v190, v191
	v_mul_f32_e32 v138, 0x3b808081, v138
	v_mul_f32_e32 v201, 0x3b808081, v190
	v_cvt_f32_ubyte2_e32 v190, v191
	v_mul_f32_e32 v204, 0x3b808081, v190
	v_cvt_f32_ubyte3_e32 v190, v191
	v_max_f32_e32 v138, 0x21800000, v138
	v_mul_f32_e32 v157, 0x3b808081, v157
	v_mul_f32_e32 v205, 0x3b808081, v190
	v_rcp_f32_e32 v190, v138
	v_max_f32_e32 v138, 0x21800000, v200
	v_rcp_f32_e32 v200, v138
	v_max_f32_e32 v138, 0x21800000, v157
	v_mul_f32_e32 v189, 0x3b808081, v189
	v_rcp_f32_e32 v191, v138
	v_max_f32_e32 v138, 0x21800000, v201
	v_rcp_f32_e32 v201, v138
	v_max_f32_e32 v138, 0x21800000, v189
	v_rcp_f32_e32 v202, v138
	v_max_f32_e32 v138, 0x21800000, v204
	v_rcp_f32_e32 v204, v138
	v_max_f32_e32 v138, 0x21800000, v203
	v_rcp_f32_e32 v203, v138
	v_cvt_f32_ubyte2_e32 v208, v182
	v_max_f32_e32 v138, 0x21800000, v205
	v_cvt_f32_ubyte1_e32 v207, v182
	v_cvt_f32_ubyte0_e32 v206, v182
	v_pk_mul_f32 v[208:209], v[208:209], s[30:31] op_sel_hi:[1,0]
	v_rcp_f32_e32 v205, v138
	v_pk_mul_f32 v[206:207], v[206:207], s[30:31] op_sel_hi:[1,0]
	v_pk_mul_f32 v[202:203], v[208:209], v[202:203]
	v_pk_mul_f32 v[190:191], v[206:207], v[190:191]
	v_pk_mul_f32 v[64:65], v[64:65], v[202:203]
	v_cvt_f32_ubyte3_e32 v203, v183
	v_cvt_f32_ubyte2_e32 v202, v183
	v_pk_mul_f32 v[62:63], v[62:63], v[190:191]
	v_cvt_f32_ubyte1_e32 v191, v183
	v_cvt_f32_ubyte0_e32 v190, v183
	v_pk_mul_f32 v[182:183], v[202:203], s[30:31] op_sel_hi:[1,0]
	v_pk_mul_f32 v[190:191], v[190:191], s[30:31] op_sel_hi:[1,0]
	v_pk_mul_f32 v[182:183], v[182:183], v[204:205]
	v_pk_mul_f32 v[190:191], v[190:191], v[200:201]
	v_pk_mul_f32 v[60:61], v[60:61], v[182:183]
	v_cvt_f32_ubyte2_e32 v182, v194
	v_mul_f32_e32 v189, 0x3b808081, v182
	v_cvt_f32_ubyte3_e32 v182, v194
	v_mul_f32_e32 v201, 0x3b808081, v182
	v_cvt_f32_ubyte0_e32 v182, v195
	v_cvt_f32_ubyte0_e32 v138, v194
	v_mul_f32_e32 v183, 0x3b808081, v182
	v_cvt_f32_ubyte1_e32 v182, v195
	v_pk_mul_f32 v[58:59], v[58:59], v[190:191]
	v_mul_f32_e32 v138, 0x3b808081, v138
	v_mul_f32_e32 v191, 0x3b808081, v182
	v_cvt_f32_ubyte2_e32 v182, v195
	v_cvt_f32_ubyte1_e32 v157, v194
	v_mul_f32_e32 v200, 0x3b808081, v182
	v_cvt_f32_ubyte3_e32 v182, v195
	v_max_f32_e32 v138, 0x21800000, v138
	v_mul_f32_e32 v157, 0x3b808081, v157
	v_mul_f32_e32 v206, 0x3b808081, v182
	v_rcp_f32_e32 v182, v138
	v_max_f32_e32 v138, 0x21800000, v183
	v_rcp_f32_e32 v190, v138
	v_max_f32_e32 v138, 0x21800000, v157
	v_rcp_f32_e32 v183, v138
	v_max_f32_e32 v138, 0x21800000, v191
	v_rcp_f32_e32 v191, v138
	v_max_f32_e32 v138, 0x21800000, v189
	v_rcp_f32_e32 v194, v138
	v_max_f32_e32 v138, 0x21800000, v200
	v_rcp_f32_e32 v200, v138
	v_max_f32_e32 v138, 0x21800000, v201
	v_cvt_f32_ubyte1_e32 v203, v192
	v_cvt_f32_ubyte0_e32 v202, v192
	v_rcp_f32_e32 v195, v138
	v_pk_mul_f32 v[202:203], v[202:203], s[30:31] op_sel_hi:[1,0]
	v_cvt_f32_ubyte3_e32 v205, v192
	v_pk_mul_f32 v[182:183], v[202:203], v[182:183]
	v_cvt_f32_ubyte2_e32 v204, v192
	v_pk_mul_f32 v[54:55], v[54:55], v[182:183]
	v_max_f32_e32 v138, 0x21800000, v206
	v_cvt_f32_ubyte1_e32 v183, v193
	v_cvt_f32_ubyte0_e32 v182, v193
	v_pk_mul_f32 v[204:205], v[204:205], s[30:31] op_sel_hi:[1,0]
	v_rcp_f32_e32 v201, v138
	v_pk_mul_f32 v[182:183], v[182:183], s[30:31] op_sel_hi:[1,0]
	v_pk_mul_f32 v[194:195], v[204:205], v[194:195]
	v_pk_mul_f32 v[182:183], v[182:183], v[190:191]
	v_pk_mul_f32 v[56:57], v[56:57], v[194:195]
	v_cvt_f32_ubyte3_e32 v195, v193
	v_cvt_f32_ubyte2_e32 v194, v193
	v_pk_mul_f32 v[50:51], v[50:51], v[182:183]
	v_cvt_f32_ubyte2_e32 v182, v198
	v_pk_mul_f32 v[192:193], v[194:195], s[30:31] op_sel_hi:[1,0]
	v_mul_f32_e32 v189, 0x3b808081, v182
	v_cvt_f32_ubyte3_e32 v182, v198
	v_pk_mul_f32 v[190:191], v[192:193], v[200:201]
	v_mul_f32_e32 v193, 0x3b808081, v182
	v_cvt_f32_ubyte0_e32 v182, v199
	v_cvt_f32_ubyte0_e32 v138, v198
	v_mul_f32_e32 v183, 0x3b808081, v182
	v_cvt_f32_ubyte1_e32 v182, v199
	v_pk_mul_f32 v[52:53], v[52:53], v[190:191]
	v_mul_f32_e32 v138, 0x3b808081, v138
	v_mul_f32_e32 v191, 0x3b808081, v182
	v_cvt_f32_ubyte2_e32 v182, v199
	v_cvt_f32_ubyte1_e32 v157, v198
	v_mul_f32_e32 v194, 0x3b808081, v182
	v_cvt_f32_ubyte3_e32 v182, v199
	v_max_f32_e32 v138, 0x21800000, v138
	v_mul_f32_e32 v157, 0x3b808081, v157
	v_mul_f32_e32 v195, 0x3b808081, v182
	v_rcp_f32_e32 v182, v138
	v_max_f32_e32 v138, 0x21800000, v183
	v_rcp_f32_e32 v190, v138
	v_max_f32_e32 v138, 0x21800000, v157
	v_rcp_f32_e32 v183, v138
	v_max_f32_e32 v138, 0x21800000, v191
	v_rcp_f32_e32 v191, v138
	v_max_f32_e32 v138, 0x21800000, v189
	v_rcp_f32_e32 v192, v138
	v_max_f32_e32 v138, 0x21800000, v194
	v_rcp_f32_e32 v194, v138
	v_max_f32_e32 v138, 0x21800000, v193
	v_rcp_f32_e32 v193, v138
	v_cvt_f32_ubyte1_e32 v199, v196
	v_cvt_f32_ubyte0_e32 v198, v196
	v_cvt_f32_ubyte3_e32 v201, v196
	v_cvt_f32_ubyte2_e32 v200, v196
	v_pk_mul_f32 v[198:199], v[198:199], s[30:31] op_sel_hi:[1,0]
	v_max_f32_e32 v138, 0x21800000, v195
	v_pk_mul_f32 v[200:201], v[200:201], s[30:31] op_sel_hi:[1,0]
	v_pk_mul_f32 v[182:183], v[198:199], v[182:183]
	v_rcp_f32_e32 v195, v138
	v_pk_mul_f32 v[192:193], v[200:201], v[192:193]
	v_pk_mul_f32 v[46:47], v[46:47], v[182:183]
	v_cvt_f32_ubyte1_e32 v183, v197
	v_cvt_f32_ubyte0_e32 v182, v197
	v_pk_mul_f32 v[48:49], v[48:49], v[192:193]
	v_cvt_f32_ubyte3_e32 v193, v197
	v_cvt_f32_ubyte2_e32 v192, v197
	v_pk_mul_f32 v[182:183], v[182:183], s[30:31] op_sel_hi:[1,0]
	v_pk_mul_f32 v[192:193], v[192:193], s[30:31] op_sel_hi:[1,0]
	v_pk_mul_f32 v[182:183], v[182:183], v[190:191]
	v_pk_mul_f32 v[190:191], v[192:193], v[194:195]
	v_pk_mul_f32 v[42:43], v[42:43], v[182:183]
	v_cvt_f32_ubyte0_e32 v138, v176
	v_cvt_f32_ubyte1_e32 v157, v176
	v_cvt_f32_ubyte2_e32 v182, v176
	v_cvt_f32_ubyte3_e32 v176, v176
	v_pk_mul_f32 v[44:45], v[44:45], v[190:191]
	v_mul_f32_e32 v191, 0x3b808081, v176
	v_cvt_f32_ubyte0_e32 v176, v177
	v_mul_f32_e32 v189, 0x3b808081, v182
	v_mul_f32_e32 v182, 0x3b808081, v176
	v_cvt_f32_ubyte1_e32 v176, v177
	v_mul_f32_e32 v138, 0x3b808081, v138
	v_mul_f32_e32 v183, 0x3b808081, v176
	v_cvt_f32_ubyte2_e32 v176, v177
	v_mul_f32_e32 v192, 0x3b808081, v176
	v_cvt_f32_ubyte3_e32 v176, v177
	v_max_f32_e32 v138, 0x21800000, v138
	v_mul_f32_e32 v157, 0x3b808081, v157
	v_mul_f32_e32 v193, 0x3b808081, v176
	v_rcp_f32_e32 v176, v138
	v_max_f32_e32 v138, 0x21800000, v182
	v_rcp_f32_e32 v182, v138
	v_max_f32_e32 v138, 0x21800000, v157
	v_rcp_f32_e32 v177, v138
	v_max_f32_e32 v138, 0x21800000, v183
	v_rcp_f32_e32 v183, v138
	v_max_f32_e32 v138, 0x21800000, v189
	v_rcp_f32_e32 v190, v138
	v_max_f32_e32 v138, 0x21800000, v192
	v_rcp_f32_e32 v192, v138
	v_max_f32_e32 v138, 0x21800000, v191
	v_rcp_f32_e32 v191, v138
	v_cvt_f32_ubyte3_e32 v197, v174
	v_cvt_f32_ubyte2_e32 v196, v174
	v_max_f32_e32 v138, 0x21800000, v193
	v_cvt_f32_ubyte1_e32 v195, v174
	v_cvt_f32_ubyte0_e32 v194, v174
	v_pk_mul_f32 v[196:197], v[196:197], s[30:31] op_sel_hi:[1,0]
	v_rcp_f32_e32 v193, v138
	v_pk_mul_f32 v[194:195], v[194:195], s[30:31] op_sel_hi:[1,0]
	v_pk_mul_f32 v[190:191], v[196:197], v[190:191]
	v_pk_mul_f32 v[176:177], v[194:195], v[176:177]
	v_pk_mul_f32 v[40:41], v[40:41], v[190:191]
	v_cvt_f32_ubyte3_e32 v191, v175
	v_cvt_f32_ubyte2_e32 v190, v175
	v_pk_mul_f32 v[38:39], v[38:39], v[176:177]
	v_cvt_f32_ubyte1_e32 v177, v175
	v_cvt_f32_ubyte0_e32 v176, v175
	v_pk_mul_f32 v[174:175], v[190:191], s[30:31] op_sel_hi:[1,0]
	v_pk_mul_f32 v[176:177], v[176:177], s[30:31] op_sel_hi:[1,0]
	v_pk_mul_f32 v[174:175], v[174:175], v[192:193]
	v_pk_mul_f32 v[176:177], v[176:177], v[182:183]
	v_pk_mul_f32 v[36:37], v[36:37], v[174:175]
	v_cvt_f32_ubyte0_e32 v138, v172
	v_cvt_f32_ubyte1_e32 v157, v172
	v_cvt_f32_ubyte2_e32 v174, v172
	v_cvt_f32_ubyte3_e32 v172, v172
	v_pk_mul_f32 v[34:35], v[34:35], v[176:177]
	v_mul_f32_e32 v177, 0x3b808081, v172
	v_cvt_f32_ubyte0_e32 v172, v173
	v_mul_f32_e32 v176, 0x3b808081, v174
	v_mul_f32_e32 v174, 0x3b808081, v172
	v_cvt_f32_ubyte1_e32 v172, v173
	v_mul_f32_e32 v138, 0x3b808081, v138
	v_mul_f32_e32 v175, 0x3b808081, v172
	v_cvt_f32_ubyte2_e32 v172, v173
	v_mul_f32_e32 v182, 0x3b808081, v172
	v_cvt_f32_ubyte3_e32 v172, v173
	v_max_f32_e32 v138, 0x21800000, v138
	v_mul_f32_e32 v157, 0x3b808081, v157
	v_mul_f32_e32 v183, 0x3b808081, v172
	v_rcp_f32_e32 v172, v138
	v_max_f32_e32 v138, 0x21800000, v174
	v_rcp_f32_e32 v174, v138
	v_max_f32_e32 v138, 0x21800000, v157
	v_rcp_f32_e32 v173, v138
	v_max_f32_e32 v138, 0x21800000, v175
	v_rcp_f32_e32 v175, v138
	v_max_f32_e32 v138, 0x21800000, v176
	v_rcp_f32_e32 v176, v138
	v_max_f32_e32 v138, 0x21800000, v182
	v_rcp_f32_e32 v182, v138
	v_max_f32_e32 v138, 0x21800000, v177
	v_rcp_f32_e32 v177, v138
	v_cvt_f32_ubyte3_e32 v193, v170
	v_cvt_f32_ubyte2_e32 v192, v170
	v_max_f32_e32 v138, 0x21800000, v183
	v_cvt_f32_ubyte1_e32 v191, v170
	v_cvt_f32_ubyte0_e32 v190, v170
	v_pk_mul_f32 v[192:193], v[192:193], s[30:31] op_sel_hi:[1,0]
	v_rcp_f32_e32 v183, v138
	v_pk_mul_f32 v[190:191], v[190:191], s[30:31] op_sel_hi:[1,0]
	v_pk_mul_f32 v[176:177], v[192:193], v[176:177]
	v_pk_mul_f32 v[172:173], v[190:191], v[172:173]
	v_pk_mul_f32 v[32:33], v[32:33], v[176:177]
	v_cvt_f32_ubyte3_e32 v177, v171
	v_cvt_f32_ubyte2_e32 v176, v171
	v_pk_mul_f32 v[30:31], v[30:31], v[172:173]
	v_cvt_f32_ubyte1_e32 v173, v171
	v_cvt_f32_ubyte0_e32 v172, v171
	v_pk_mul_f32 v[170:171], v[176:177], s[30:31] op_sel_hi:[1,0]
	v_pk_mul_f32 v[172:173], v[172:173], s[30:31] op_sel_hi:[1,0]
	v_pk_mul_f32 v[170:171], v[170:171], v[182:183]
	v_pk_mul_f32 v[172:173], v[172:173], v[174:175]
	v_pk_mul_f32 v[28:29], v[28:29], v[170:171]
	v_cvt_f32_ubyte0_e32 v138, v168
	v_cvt_f32_ubyte1_e32 v157, v168
	v_cvt_f32_ubyte2_e32 v170, v168
	v_cvt_f32_ubyte3_e32 v168, v168
	v_pk_mul_f32 v[26:27], v[26:27], v[172:173]
	v_mul_f32_e32 v173, 0x3b808081, v168
	v_cvt_f32_ubyte0_e32 v168, v169
	v_mul_f32_e32 v172, 0x3b808081, v170
	v_mul_f32_e32 v170, 0x3b808081, v168
	v_cvt_f32_ubyte1_e32 v168, v169
	v_mul_f32_e32 v138, 0x3b808081, v138
	v_mul_f32_e32 v171, 0x3b808081, v168
	v_cvt_f32_ubyte2_e32 v168, v169
	v_mul_f32_e32 v174, 0x3b808081, v168
	v_cvt_f32_ubyte3_e32 v168, v169
	v_max_f32_e32 v138, 0x21800000, v138
	v_mul_f32_e32 v157, 0x3b808081, v157
	v_mul_f32_e32 v175, 0x3b808081, v168
	v_rcp_f32_e32 v168, v138
	v_max_f32_e32 v138, 0x21800000, v170
	v_rcp_f32_e32 v170, v138
	v_max_f32_e32 v138, 0x21800000, v157
	v_rcp_f32_e32 v169, v138
	v_max_f32_e32 v138, 0x21800000, v171
	v_rcp_f32_e32 v171, v138
	v_max_f32_e32 v138, 0x21800000, v172
	v_rcp_f32_e32 v172, v138
	v_max_f32_e32 v138, 0x21800000, v174
	v_rcp_f32_e32 v174, v138
	v_max_f32_e32 v138, 0x21800000, v173
	v_rcp_f32_e32 v173, v138
	v_cvt_f32_ubyte3_e32 v183, v166
	v_cvt_f32_ubyte2_e32 v182, v166
	v_max_f32_e32 v138, 0x21800000, v175
	v_cvt_f32_ubyte1_e32 v177, v166
	v_cvt_f32_ubyte0_e32 v176, v166
	v_pk_mul_f32 v[182:183], v[182:183], s[30:31] op_sel_hi:[1,0]
	v_rcp_f32_e32 v175, v138
	v_pk_mul_f32 v[176:177], v[176:177], s[30:31] op_sel_hi:[1,0]
	v_pk_mul_f32 v[172:173], v[182:183], v[172:173]
	v_pk_mul_f32 v[168:169], v[176:177], v[168:169]
	v_pk_mul_f32 v[24:25], v[24:25], v[172:173]
	v_cvt_f32_ubyte3_e32 v173, v167
	v_cvt_f32_ubyte2_e32 v172, v167
	v_pk_mul_f32 v[22:23], v[22:23], v[168:169]
	v_cvt_f32_ubyte1_e32 v169, v167
	v_cvt_f32_ubyte0_e32 v168, v167
	v_pk_mul_f32 v[166:167], v[172:173], s[30:31] op_sel_hi:[1,0]
	v_pk_mul_f32 v[168:169], v[168:169], s[30:31] op_sel_hi:[1,0]
	v_pk_mul_f32 v[166:167], v[166:167], v[174:175]
	v_pk_mul_f32 v[168:169], v[168:169], v[170:171]
	v_pk_mul_f32 v[20:21], v[20:21], v[166:167]
	v_cvt_f32_ubyte0_e32 v138, v164
	v_cvt_f32_ubyte1_e32 v157, v164
	v_cvt_f32_ubyte2_e32 v166, v164
	v_cvt_f32_ubyte3_e32 v164, v164
	v_pk_mul_f32 v[18:19], v[18:19], v[168:169]
	v_mul_f32_e32 v169, 0x3b808081, v164
	v_cvt_f32_ubyte0_e32 v164, v165
	v_mul_f32_e32 v168, 0x3b808081, v166
	v_mul_f32_e32 v166, 0x3b808081, v164
	v_cvt_f32_ubyte1_e32 v164, v165
	v_mul_f32_e32 v138, 0x3b808081, v138
	v_mul_f32_e32 v167, 0x3b808081, v164
	v_cvt_f32_ubyte2_e32 v164, v165
	v_mul_f32_e32 v170, 0x3b808081, v164
	v_cvt_f32_ubyte3_e32 v164, v165
	v_max_f32_e32 v138, 0x21800000, v138
	v_mul_f32_e32 v157, 0x3b808081, v157
	v_mul_f32_e32 v171, 0x3b808081, v164
	v_rcp_f32_e32 v164, v138
	v_max_f32_e32 v138, 0x21800000, v166
	v_rcp_f32_e32 v166, v138
	v_max_f32_e32 v138, 0x21800000, v157
	v_rcp_f32_e32 v165, v138
	v_max_f32_e32 v138, 0x21800000, v167
	v_rcp_f32_e32 v167, v138
	v_max_f32_e32 v138, 0x21800000, v168
	v_rcp_f32_e32 v168, v138
	v_max_f32_e32 v138, 0x21800000, v170
	v_rcp_f32_e32 v170, v138
	v_max_f32_e32 v138, 0x21800000, v169
	v_rcp_f32_e32 v169, v138
	v_cvt_f32_ubyte3_e32 v175, v162
	v_cvt_f32_ubyte2_e32 v174, v162
	v_max_f32_e32 v138, 0x21800000, v171
	v_cvt_f32_ubyte1_e32 v173, v162
	v_cvt_f32_ubyte0_e32 v172, v162
	v_pk_mul_f32 v[174:175], v[174:175], s[30:31] op_sel_hi:[1,0]
	v_rcp_f32_e32 v171, v138
	v_pk_mul_f32 v[172:173], v[172:173], s[30:31] op_sel_hi:[1,0]
	v_pk_mul_f32 v[168:169], v[174:175], v[168:169]
	v_pk_mul_f32 v[164:165], v[172:173], v[164:165]
	v_pk_mul_f32 v[16:17], v[16:17], v[168:169]
	v_cvt_f32_ubyte3_e32 v169, v163
	v_cvt_f32_ubyte2_e32 v168, v163
	v_pk_mul_f32 v[14:15], v[14:15], v[164:165]
	v_cvt_f32_ubyte1_e32 v165, v163
	v_cvt_f32_ubyte0_e32 v164, v163
	v_pk_mul_f32 v[162:163], v[168:169], s[30:31] op_sel_hi:[1,0]
	v_pk_mul_f32 v[164:165], v[164:165], s[30:31] op_sel_hi:[1,0]
	v_pk_mul_f32 v[162:163], v[162:163], v[170:171]
	v_pk_mul_f32 v[164:165], v[164:165], v[166:167]
	v_pk_mul_f32 v[12:13], v[12:13], v[162:163]
	v_cvt_f32_ubyte0_e32 v138, v160
	v_cvt_f32_ubyte1_e32 v157, v160
	v_cvt_f32_ubyte2_e32 v162, v160
	v_cvt_f32_ubyte3_e32 v160, v160
	v_pk_mul_f32 v[10:11], v[10:11], v[164:165]
	v_mul_f32_e32 v165, 0x3b808081, v160
	v_cvt_f32_ubyte0_e32 v160, v161
	v_mul_f32_e32 v164, 0x3b808081, v162
	v_mul_f32_e32 v162, 0x3b808081, v160
	v_cvt_f32_ubyte1_e32 v160, v161
	v_mul_f32_e32 v138, 0x3b808081, v138
	v_mul_f32_e32 v163, 0x3b808081, v160
	v_cvt_f32_ubyte2_e32 v160, v161
	v_mul_f32_e32 v166, 0x3b808081, v160
	v_cvt_f32_ubyte3_e32 v160, v161
	v_max_f32_e32 v138, 0x21800000, v138
	v_mul_f32_e32 v157, 0x3b808081, v157
	v_mul_f32_e32 v167, 0x3b808081, v160
	v_rcp_f32_e32 v160, v138
	v_max_f32_e32 v138, 0x21800000, v162
	v_rcp_f32_e32 v162, v138
	v_max_f32_e32 v138, 0x21800000, v157
	v_rcp_f32_e32 v161, v138
	v_max_f32_e32 v138, 0x21800000, v163
	v_rcp_f32_e32 v163, v138
	v_max_f32_e32 v138, 0x21800000, v164
	v_rcp_f32_e32 v164, v138
	v_max_f32_e32 v138, 0x21800000, v166
	v_rcp_f32_e32 v166, v138
	v_max_f32_e32 v138, 0x21800000, v165
	v_rcp_f32_e32 v165, v138
	v_cvt_f32_ubyte1_e32 v169, v158
	v_cvt_f32_ubyte0_e32 v168, v158
	v_cvt_f32_ubyte3_e32 v171, v158
	v_cvt_f32_ubyte2_e32 v170, v158
	v_max_f32_e32 v138, 0x21800000, v167
	v_pk_mul_f32 v[170:171], v[170:171], s[30:31] op_sel_hi:[1,0]
	v_pk_mul_f32 v[168:169], v[168:169], s[30:31] op_sel_hi:[1,0]
	v_rcp_f32_e32 v167, v138
	v_pk_mul_f32 v[160:161], v[168:169], v[160:161]
	v_pk_mul_f32 v[164:165], v[170:171], v[164:165]
	v_pk_mul_f32 v[6:7], v[6:7], v[160:161]
	v_pk_mul_f32 v[8:9], v[8:9], v[164:165]
	v_cvt_f32_ubyte1_e32 v161, v159
	v_cvt_f32_ubyte0_e32 v160, v159
	v_cvt_f32_ubyte3_e32 v165, v159
	v_cvt_f32_ubyte2_e32 v164, v159
	v_pk_mul_f32 v[158:159], v[164:165], s[30:31] op_sel_hi:[1,0]
	v_pk_mul_f32 v[160:161], v[160:161], s[30:31] op_sel_hi:[1,0]
	v_pk_mul_f32 v[158:159], v[158:159], v[166:167]
	v_pk_mul_f32 v[160:161], v[160:161], v[162:163]
	v_pk_mul_f32 v[4:5], v[4:5], v[158:159]
	v_pk_mul_f32 v[2:3], v[2:3], v[160:161]
	s_cbranch_scc1 .LBB0_829
	s_ashr_i32 s41, s40, 31
	s_lshl_b64 s[0:1], s[40:41], 7
	s_add_u32 s0, s0, 0x100
	s_addc_u32 s1, s1, 0
